# strategy 4 at one more site: static priority raise for waves 4-7 also at the cmp1_fused unit loop (P6), on top of v025
# speedup vs baseline: 1.0047x; 1.0047x over previous
; #define LAS __attribute__((address_space(3)))
; __device__ __forceinline__ void cmp1_fused(const P& p, Frame& F) {
;     ...
;     int tid = threadIdx.x; asm volatile("" : "+v"(tid));
;     const int lane = tid & 63, wave = __builtin_amdgcn_readfirstlane(tid >> 6), ql = lane & 31, half = lane >> 5, l16 = tid & 15, r32 = tid >> 4, p8 = tid & 7, r64 = tid >> 3;
;     const bool pth = lane < 8; const int pr = wave, pp = lane & 7;
;     LAS unsigned char* L = F.lds;
;     __syncthreads();
;     for (int unit = F.bid; unit < 256; unit += F.G) {
;         const int kv = unit >> 7, blk = unit & 127;
.LBB0_1419:
	v_readfirstlane_b32 s26, v0
	s_nop 3
	s_bitcmp1_b32 s26, 8
	s_cbranch_scc0 .Lprio_p6_done
	s_setprio 1
